# decode pass A: two K register buffers (second one in the idle V-stage registers), next-next tile load issued as each piece is parked: 8-16 K loads in flight per wave
# baseline (speedup 1.0000x reference)
.Ldc_nopf:
	s_ashr_i32 s7, s6, 31
	s_lshl_b64 s[6:7], s[6:7], 19
	s_add_u32 s12, s80, s6
	s_addc_u32 s13, s81, s7
	s_and_b32 s13, s13, 0xffff
	buffer_load_dwordx4 v[42:45], v247, s[12:15], 0 offen nt
	buffer_load_dwordx4 v[46:49], v247, s[12:15], s43 offen nt
	buffer_load_dwordx4 v[50:53], v247, s[12:15], s46 offen nt
	buffer_load_dwordx4 v[54:57], v247, s[12:15], s47 offen nt
	buffer_load_dwordx4 v[58:61], v247, s[12:15], s16 offen nt
	s_movk_i32 s16, 0x4800
	buffer_load_dwordx4 v[62:65], v247, s[12:15], s16 offen nt
	s_mov_b32 s16, 0x8800
	buffer_load_dwordx4 v[66:69], v247, s[12:15], s16 offen nt
	s_mov_b32 s16, 0xc800
	buffer_load_dwordx4 v[70:73], v247, s[12:15], s16 offen nt
	buffer_load_dwordx4 v[86:89], v247, s[12:15], s48 offen nt
	buffer_load_dwordx4 v[90:93], v247, s[12:15], s49 offen nt
	buffer_load_dwordx4 v[94:97], v247, s[12:15], s50 offen nt
	buffer_load_dwordx4 v[98:101], v247, s[12:15], s51 offen nt
	s_mov_b32 s99, 0x10800
	buffer_load_dwordx4 v[102:105], v247, s[12:15], s99 offen nt
	s_mov_b32 s99, 0x14800
	buffer_load_dwordx4 v[106:109], v247, s[12:15], s99 offen nt
	s_mov_b32 s99, 0x18800
	buffer_load_dwordx4 v[110:113], v247, s[12:15], s99 offen nt
	s_mov_b32 s99, 0x1c800
	buffer_load_dwordx4 v[114:117], v247, s[12:15], s99 offen nt
	s_mov_b32 s16, 0x10800
	s_waitcnt vmcnt(15)
	v_cvt_pk_bf16_f32 v74, v42, v43
	v_cvt_pk_bf16_f32 v75, v44, v45
	ds_write_b64 v249, v[74:75]
	buffer_load_dwordx4 v[42:45], v247, s[12:15], s15 offen nt
	s_waitcnt vmcnt(15)
	v_cvt_pk_bf16_f32 v74, v46, v47
	v_cvt_pk_bf16_f32 v75, v48, v49
	ds_write_b64 v249, v[74:75] offset:576
	buffer_load_dwordx4 v[46:49], v247, s[12:15], s52 offen nt
	s_waitcnt vmcnt(15)
	v_cvt_pk_bf16_f32 v74, v50, v51
	v_cvt_pk_bf16_f32 v75, v52, v53
	ds_write_b64 v249, v[74:75] offset:1152
	buffer_load_dwordx4 v[50:53], v247, s[12:15], s53 offen nt
	s_waitcnt vmcnt(15)
	v_cvt_pk_bf16_f32 v74, v54, v55
	v_cvt_pk_bf16_f32 v75, v56, v57
	ds_write_b64 v249, v[74:75] offset:1728
	buffer_load_dwordx4 v[54:57], v247, s[12:15], s54 offen nt
	s_waitcnt vmcnt(15)
	v_cvt_pk_bf16_f32 v74, v58, v59
	v_cvt_pk_bf16_f32 v75, v60, v61
	ds_write_b64 v249, v[74:75] offset:2304
	s_mov_b32 s99, 0x20800
	buffer_load_dwordx4 v[58:61], v247, s[12:15], s99 offen nt
	s_waitcnt vmcnt(15)
	v_cvt_pk_bf16_f32 v74, v62, v63
	v_cvt_pk_bf16_f32 v75, v64, v65
	ds_write_b64 v249, v[74:75] offset:2880
	s_mov_b32 s99, 0x24800
	buffer_load_dwordx4 v[62:65], v247, s[12:15], s99 offen nt
	s_waitcnt vmcnt(15)
	v_cvt_pk_bf16_f32 v74, v66, v67
	v_cvt_pk_bf16_f32 v75, v68, v69
	ds_write_b64 v249, v[74:75] offset:3456
	s_mov_b32 s99, 0x28800
	buffer_load_dwordx4 v[66:69], v247, s[12:15], s99 offen nt
	s_waitcnt vmcnt(15)
	v_cvt_pk_bf16_f32 v74, v70, v71
	v_cvt_pk_bf16_f32 v75, v72, v73
	ds_write_b64 v249, v[74:75] offset:4032
	s_mov_b32 s99, 0x2c800
	buffer_load_dwordx4 v[70:73], v247, s[12:15], s99 offen nt
	s_waitcnt lgkmcnt(0)
	ds_read_b128 v[74:77], v250
	ds_read_b128 v[78:81], v250 offset:64
	s_waitcnt lgkmcnt(1)
	v_mfma_f32_16x16x32_bf16 v[74:77], v[74:77], v[2:5], 0
	ds_read_b128 v[82:85], v250 offset:2304
	s_add_u32 s16, s82, s6
	s_addc_u32 s6, s83, s7
	s_waitcnt lgkmcnt(1)
	v_mfma_f32_16x16x32_bf16 v[74:77], v[78:81], v[6:9], v[74:77]
	ds_read_b128 v[78:81], v250 offset:2368
	s_waitcnt lgkmcnt(1)
	v_mfma_f32_16x16x32_bf16 v[82:85], v[82:85], v[2:5], 0
	s_waitcnt lgkmcnt(0)
	v_mfma_f32_16x16x32_bf16 v[78:81], v[78:81], v[6:9], v[82:85]
	s_nop 7
	v_cndmask_b32_e64 v205, v81, v77, s[2:3]
	v_cndmask_b32_e64 v204, v80, v76, s[2:3]
	v_cndmask_b32_e64 v207, v79, v75, s[2:3]
	v_cndmask_b32_e64 v206, v78, v74, s[2:3]
	s_waitcnt vmcnt(15)
	v_cvt_pk_bf16_f32 v74, v86, v87
	v_cvt_pk_bf16_f32 v75, v88, v89
	ds_write_b64 v249, v[74:75] offset:4608
	buffer_load_dwordx4 v[86:89], v247, s[12:15], s55 offen nt
	s_waitcnt vmcnt(15)
	v_cvt_pk_bf16_f32 v74, v90, v91
	v_cvt_pk_bf16_f32 v75, v92, v93
	ds_write_b64 v249, v[74:75] offset:5184
	buffer_load_dwordx4 v[90:93], v247, s[12:15], s56 offen nt
	s_waitcnt vmcnt(15)
	v_cvt_pk_bf16_f32 v74, v94, v95
	v_cvt_pk_bf16_f32 v75, v96, v97
	ds_write_b64 v249, v[74:75] offset:5760
	buffer_load_dwordx4 v[94:97], v247, s[12:15], s57 offen nt
	s_waitcnt vmcnt(15)
	v_cvt_pk_bf16_f32 v74, v98, v99
	v_cvt_pk_bf16_f32 v75, v100, v101
	ds_write_b64 v249, v[74:75] offset:6336
	buffer_load_dwordx4 v[98:101], v247, s[12:15], s62 offen nt
	s_waitcnt vmcnt(15)
	v_cvt_pk_bf16_f32 v74, v102, v103
	v_cvt_pk_bf16_f32 v75, v104, v105
	ds_write_b64 v249, v[74:75] offset:6912
	s_mov_b32 s99, 0x30800
	buffer_load_dwordx4 v[102:105], v247, s[12:15], s99 offen nt
	s_waitcnt vmcnt(15)
	v_cvt_pk_bf16_f32 v74, v106, v107
	v_cvt_pk_bf16_f32 v75, v108, v109
	ds_write_b64 v249, v[74:75] offset:7488
	s_mov_b32 s99, 0x34800
	buffer_load_dwordx4 v[106:109], v247, s[12:15], s99 offen nt
	s_waitcnt vmcnt(15)
	v_cvt_pk_bf16_f32 v74, v110, v111
	v_cvt_pk_bf16_f32 v75, v112, v113
	ds_write_b64 v249, v[74:75] offset:8064
	s_mov_b32 s99, 0x38800
	buffer_load_dwordx4 v[110:113], v247, s[12:15], s99 offen nt
	s_waitcnt vmcnt(15)
	v_cvt_pk_bf16_f32 v74, v114, v115
	v_cvt_pk_bf16_f32 v75, v116, v117
	ds_write_b64 v249, v[74:75] offset:8640
	s_mov_b32 s99, 0x3c800
	buffer_load_dwordx4 v[114:117], v247, s[12:15], s99 offen nt
	s_waitcnt lgkmcnt(0)
	ds_read_b128 v[74:77], v250 offset:4608
	ds_read_b128 v[78:81], v250 offset:4672
	s_waitcnt lgkmcnt(1)
	v_mfma_f32_16x16x32_bf16 v[74:77], v[74:77], v[2:5], 0
	ds_read_b128 v[82:85], v250 offset:6912
	s_waitcnt lgkmcnt(1)
	v_mfma_f32_16x16x32_bf16 v[74:77], v[78:81], v[6:9], v[74:77]
	ds_read_b128 v[78:81], v250 offset:6976
	s_waitcnt lgkmcnt(1)
	v_mfma_f32_16x16x32_bf16 v[82:85], v[82:85], v[2:5], 0
	s_waitcnt lgkmcnt(0)
	v_mfma_f32_16x16x32_bf16 v[78:81], v[78:81], v[6:9], v[82:85]
	s_nop 7
	v_cndmask_b32_e64 v209, v81, v77, s[2:3]
	v_cndmask_b32_e64 v208, v80, v76, s[2:3]
	v_cndmask_b32_e64 v211, v79, v75, s[2:3]
	v_cndmask_b32_e64 v210, v78, v74, s[2:3]
	s_waitcnt vmcnt(15)
	v_cvt_pk_bf16_f32 v74, v42, v43
	v_cvt_pk_bf16_f32 v75, v44, v45
	ds_write_b64 v249, v[74:75]
	buffer_load_dwordx4 v[42:45], v247, s[12:15], s63 offen nt
	s_waitcnt vmcnt(15)
	v_cvt_pk_bf16_f32 v74, v46, v47
	v_cvt_pk_bf16_f32 v75, v48, v49
	ds_write_b64 v249, v[74:75] offset:576
	buffer_load_dwordx4 v[46:49], v247, s[12:15], s64 offen nt
	s_waitcnt vmcnt(15)
	v_cvt_pk_bf16_f32 v74, v50, v51
	v_cvt_pk_bf16_f32 v75, v52, v53
	ds_write_b64 v249, v[74:75] offset:1152
	buffer_load_dwordx4 v[50:53], v247, s[12:15], s65 offen nt
	s_waitcnt vmcnt(15)
	v_cvt_pk_bf16_f32 v74, v54, v55
	v_cvt_pk_bf16_f32 v75, v56, v57
	ds_write_b64 v249, v[74:75] offset:1728
	buffer_load_dwordx4 v[54:57], v247, s[12:15], s66 offen nt
	s_waitcnt vmcnt(15)
	v_cvt_pk_bf16_f32 v74, v58, v59
	v_cvt_pk_bf16_f32 v75, v60, v61
	ds_write_b64 v249, v[74:75] offset:2304
	s_mov_b32 s99, 0x40800
	buffer_load_dwordx4 v[58:61], v247, s[12:15], s99 offen nt
	s_waitcnt vmcnt(15)
	v_cvt_pk_bf16_f32 v74, v62, v63
	v_cvt_pk_bf16_f32 v75, v64, v65
	ds_write_b64 v249, v[74:75] offset:2880
	s_mov_b32 s99, 0x44800
	buffer_load_dwordx4 v[62:65], v247, s[12:15], s99 offen nt
	s_waitcnt vmcnt(15)
	v_cvt_pk_bf16_f32 v74, v66, v67
	v_cvt_pk_bf16_f32 v75, v68, v69
	ds_write_b64 v249, v[74:75] offset:3456
	s_mov_b32 s99, 0x48800
	buffer_load_dwordx4 v[66:69], v247, s[12:15], s99 offen nt
	s_waitcnt vmcnt(15)
	v_cvt_pk_bf16_f32 v74, v70, v71
	v_cvt_pk_bf16_f32 v75, v72, v73
	ds_write_b64 v249, v[74:75] offset:4032
	s_mov_b32 s99, 0x4c800
	buffer_load_dwordx4 v[70:73], v247, s[12:15], s99 offen nt
	s_waitcnt lgkmcnt(0)
	ds_read_b128 v[74:77], v250
	ds_read_b128 v[78:81], v250 offset:64
	s_waitcnt lgkmcnt(1)
	v_mfma_f32_16x16x32_bf16 v[74:77], v[74:77], v[2:5], 0
	ds_read_b128 v[82:85], v250 offset:2304
	s_waitcnt lgkmcnt(1)
	v_mfma_f32_16x16x32_bf16 v[74:77], v[78:81], v[6:9], v[74:77]
	ds_read_b128 v[78:81], v250 offset:2368
	s_waitcnt lgkmcnt(1)
	v_mfma_f32_16x16x32_bf16 v[82:85], v[82:85], v[2:5], 0
	s_waitcnt lgkmcnt(0)
	v_mfma_f32_16x16x32_bf16 v[78:81], v[78:81], v[6:9], v[82:85]
	s_nop 7
	v_cndmask_b32_e64 v213, v81, v77, s[2:3]
	v_cndmask_b32_e64 v212, v80, v76, s[2:3]
	v_cndmask_b32_e64 v215, v79, v75, s[2:3]
	v_cndmask_b32_e64 v214, v78, v74, s[2:3]
	s_waitcnt vmcnt(15)
	v_cvt_pk_bf16_f32 v74, v86, v87
	v_cvt_pk_bf16_f32 v75, v88, v89
	ds_write_b64 v249, v[74:75] offset:4608
	buffer_load_dwordx4 v[86:89], v247, s[12:15], s67 offen nt
	s_waitcnt vmcnt(15)
	v_cvt_pk_bf16_f32 v74, v90, v91
	v_cvt_pk_bf16_f32 v75, v92, v93
	ds_write_b64 v249, v[74:75] offset:5184
	buffer_load_dwordx4 v[90:93], v247, s[12:15], s68 offen nt
	s_waitcnt vmcnt(15)
	v_cvt_pk_bf16_f32 v74, v94, v95
	v_cvt_pk_bf16_f32 v75, v96, v97
	ds_write_b64 v249, v[74:75] offset:5760
	buffer_load_dwordx4 v[94:97], v247, s[12:15], s69 offen nt
	s_waitcnt vmcnt(15)
	v_cvt_pk_bf16_f32 v74, v98, v99
	v_cvt_pk_bf16_f32 v75, v100, v101
	ds_write_b64 v249, v[74:75] offset:6336
	buffer_load_dwordx4 v[98:101], v247, s[12:15], s84 offen nt
	s_waitcnt vmcnt(15)
	v_cvt_pk_bf16_f32 v74, v102, v103
	v_cvt_pk_bf16_f32 v75, v104, v105
	ds_write_b64 v249, v[74:75] offset:6912
	s_mov_b32 s99, 0x50800
	buffer_load_dwordx4 v[102:105], v247, s[12:15], s99 offen nt
	s_waitcnt vmcnt(15)
	v_cvt_pk_bf16_f32 v74, v106, v107
	v_cvt_pk_bf16_f32 v75, v108, v109
	ds_write_b64 v249, v[74:75] offset:7488
	s_mov_b32 s99, 0x54800
	buffer_load_dwordx4 v[106:109], v247, s[12:15], s99 offen nt
	s_waitcnt vmcnt(15)
	v_cvt_pk_bf16_f32 v74, v110, v111
	v_cvt_pk_bf16_f32 v75, v112, v113
	ds_write_b64 v249, v[74:75] offset:8064
	s_mov_b32 s99, 0x58800
	buffer_load_dwordx4 v[110:113], v247, s[12:15], s99 offen nt
	s_waitcnt vmcnt(15)
	v_cvt_pk_bf16_f32 v74, v114, v115
	v_cvt_pk_bf16_f32 v75, v116, v117
	ds_write_b64 v249, v[74:75] offset:8640
	s_mov_b32 s99, 0x5c800
	buffer_load_dwordx4 v[114:117], v247, s[12:15], s99 offen nt
	s_waitcnt lgkmcnt(0)
	ds_read_b128 v[74:77], v250 offset:4608
	ds_read_b128 v[78:81], v250 offset:4672
	s_waitcnt lgkmcnt(1)
	v_mfma_f32_16x16x32_bf16 v[74:77], v[74:77], v[2:5], 0
	ds_read_b128 v[82:85], v250 offset:6912
	s_waitcnt lgkmcnt(1)
	v_mfma_f32_16x16x32_bf16 v[74:77], v[78:81], v[6:9], v[74:77]
	ds_read_b128 v[78:81], v250 offset:6976
	s_waitcnt lgkmcnt(1)
	v_mfma_f32_16x16x32_bf16 v[82:85], v[82:85], v[2:5], 0
	s_waitcnt lgkmcnt(0)
	v_mfma_f32_16x16x32_bf16 v[78:81], v[78:81], v[6:9], v[82:85]
	s_nop 7
	v_cndmask_b32_e64 v217, v81, v77, s[2:3]
	v_cndmask_b32_e64 v216, v80, v76, s[2:3]
	v_cndmask_b32_e64 v219, v79, v75, s[2:3]
	v_cndmask_b32_e64 v218, v78, v74, s[2:3]
	s_waitcnt vmcnt(15)
	v_cvt_pk_bf16_f32 v74, v42, v43
	v_cvt_pk_bf16_f32 v75, v44, v45
	ds_write_b64 v249, v[74:75]
	buffer_load_dwordx4 v[42:45], v247, s[12:15], s85 offen nt
	s_waitcnt vmcnt(15)
	v_cvt_pk_bf16_f32 v74, v46, v47
	v_cvt_pk_bf16_f32 v75, v48, v49
	ds_write_b64 v249, v[74:75] offset:576
	buffer_load_dwordx4 v[46:49], v247, s[12:15], s86 offen nt
	s_waitcnt vmcnt(15)
	v_cvt_pk_bf16_f32 v74, v50, v51
	v_cvt_pk_bf16_f32 v75, v52, v53
	ds_write_b64 v249, v[74:75] offset:1152
	buffer_load_dwordx4 v[50:53], v247, s[12:15], s87 offen nt
	s_waitcnt vmcnt(15)
	v_cvt_pk_bf16_f32 v74, v54, v55
	v_cvt_pk_bf16_f32 v75, v56, v57
	ds_write_b64 v249, v[74:75] offset:1728
	buffer_load_dwordx4 v[54:57], v247, s[12:15], s92 offen nt
	s_waitcnt vmcnt(15)
	v_cvt_pk_bf16_f32 v74, v58, v59
	v_cvt_pk_bf16_f32 v75, v60, v61
	ds_write_b64 v249, v[74:75] offset:2304
	s_mov_b32 s99, 0x60800
	buffer_load_dwordx4 v[58:61], v247, s[12:15], s99 offen nt
	s_waitcnt vmcnt(15)
	v_cvt_pk_bf16_f32 v74, v62, v63
	v_cvt_pk_bf16_f32 v75, v64, v65
	ds_write_b64 v249, v[74:75] offset:2880
	s_mov_b32 s99, 0x64800
	buffer_load_dwordx4 v[62:65], v247, s[12:15], s99 offen nt
	s_waitcnt vmcnt(15)
	v_cvt_pk_bf16_f32 v74, v66, v67
	v_cvt_pk_bf16_f32 v75, v68, v69
	ds_write_b64 v249, v[74:75] offset:3456
	s_mov_b32 s99, 0x68800
	buffer_load_dwordx4 v[66:69], v247, s[12:15], s99 offen nt
	s_waitcnt vmcnt(15)
	v_cvt_pk_bf16_f32 v74, v70, v71
	v_cvt_pk_bf16_f32 v75, v72, v73
	ds_write_b64 v249, v[74:75] offset:4032
	s_mov_b32 s99, 0x6c800
	buffer_load_dwordx4 v[70:73], v247, s[12:15], s99 offen nt
	s_waitcnt lgkmcnt(0)
	ds_read_b128 v[74:77], v250
	ds_read_b128 v[78:81], v250 offset:64
	s_waitcnt lgkmcnt(1)
	v_mfma_f32_16x16x32_bf16 v[74:77], v[74:77], v[2:5], 0
	ds_read_b128 v[82:85], v250 offset:2304
	s_waitcnt lgkmcnt(1)
	v_mfma_f32_16x16x32_bf16 v[74:77], v[78:81], v[6:9], v[74:77]
	ds_read_b128 v[78:81], v250 offset:2368
	s_waitcnt lgkmcnt(1)
	v_mfma_f32_16x16x32_bf16 v[82:85], v[82:85], v[2:5], 0
	s_waitcnt lgkmcnt(0)
	v_mfma_f32_16x16x32_bf16 v[78:81], v[78:81], v[6:9], v[82:85]
	s_nop 7
	v_cndmask_b32_e64 v221, v81, v77, s[2:3]
	v_cndmask_b32_e64 v220, v80, v76, s[2:3]
	v_cndmask_b32_e64 v223, v79, v75, s[2:3]
	v_cndmask_b32_e64 v222, v78, v74, s[2:3]
	s_waitcnt vmcnt(15)
	v_cvt_pk_bf16_f32 v74, v86, v87
	v_cvt_pk_bf16_f32 v75, v88, v89
	ds_write_b64 v249, v[74:75] offset:4608
	buffer_load_dwordx4 v[86:89], v247, s[12:15], s94 offen nt
	s_waitcnt vmcnt(15)
	v_cvt_pk_bf16_f32 v74, v90, v91
	v_cvt_pk_bf16_f32 v75, v92, v93
	ds_write_b64 v249, v[74:75] offset:5184
	buffer_load_dwordx4 v[90:93], v247, s[12:15], s95 offen nt
	s_waitcnt vmcnt(15)
	v_cvt_pk_bf16_f32 v74, v94, v95
	v_cvt_pk_bf16_f32 v75, v96, v97
	ds_write_b64 v249, v[74:75] offset:5760
	buffer_load_dwordx4 v[94:97], v247, s[12:15], s96 offen nt
	s_waitcnt vmcnt(15)
	v_cvt_pk_bf16_f32 v74, v98, v99
	v_cvt_pk_bf16_f32 v75, v100, v101
	ds_write_b64 v249, v[74:75] offset:6336
	buffer_load_dwordx4 v[98:101], v247, s[12:15], s97 offen nt
	s_waitcnt vmcnt(15)
	v_cvt_pk_bf16_f32 v74, v102, v103
	v_cvt_pk_bf16_f32 v75, v104, v105
	ds_write_b64 v249, v[74:75] offset:6912
	s_mov_b32 s99, 0x70800
	buffer_load_dwordx4 v[102:105], v247, s[12:15], s99 offen nt
	s_waitcnt vmcnt(15)
	v_cvt_pk_bf16_f32 v74, v106, v107
	v_cvt_pk_bf16_f32 v75, v108, v109
	ds_write_b64 v249, v[74:75] offset:7488
	s_mov_b32 s99, 0x74800
	buffer_load_dwordx4 v[106:109], v247, s[12:15], s99 offen nt
	s_waitcnt vmcnt(15)
	v_cvt_pk_bf16_f32 v74, v110, v111
	v_cvt_pk_bf16_f32 v75, v112, v113
	ds_write_b64 v249, v[74:75] offset:8064
	s_mov_b32 s99, 0x78800
	buffer_load_dwordx4 v[110:113], v247, s[12:15], s99 offen nt
	s_waitcnt vmcnt(15)
	v_cvt_pk_bf16_f32 v74, v114, v115
	v_cvt_pk_bf16_f32 v75, v116, v117
	ds_write_b64 v249, v[74:75] offset:8640
	s_mov_b32 s99, 0x7c800
	buffer_load_dwordx4 v[114:117], v247, s[12:15], s99 offen nt
	s_waitcnt lgkmcnt(0)
	ds_read_b128 v[74:77], v250 offset:4608
	ds_read_b128 v[78:81], v250 offset:4672
	s_waitcnt lgkmcnt(1)
	v_mfma_f32_16x16x32_bf16 v[74:77], v[74:77], v[2:5], 0
	ds_read_b128 v[82:85], v250 offset:6912
	s_waitcnt lgkmcnt(1)
	v_mfma_f32_16x16x32_bf16 v[74:77], v[78:81], v[6:9], v[74:77]
	ds_read_b128 v[78:81], v250 offset:6976
	s_waitcnt lgkmcnt(1)
	v_mfma_f32_16x16x32_bf16 v[82:85], v[82:85], v[2:5], 0
	s_waitcnt lgkmcnt(0)
	v_mfma_f32_16x16x32_bf16 v[78:81], v[78:81], v[6:9], v[82:85]
	s_nop 7
	v_cndmask_b32_e64 v225, v81, v77, s[2:3]
	v_cndmask_b32_e64 v224, v80, v76, s[2:3]
	v_cndmask_b32_e64 v227, v79, v75, s[2:3]
	v_cndmask_b32_e64 v226, v78, v74, s[2:3]
	s_waitcnt vmcnt(15)
	v_cvt_pk_bf16_f32 v74, v42, v43
	v_cvt_pk_bf16_f32 v75, v44, v45
	ds_write_b64 v249, v[74:75]
	s_waitcnt vmcnt(14)
	v_cvt_pk_bf16_f32 v74, v46, v47
	v_cvt_pk_bf16_f32 v75, v48, v49
	ds_write_b64 v249, v[74:75] offset:576
	s_waitcnt vmcnt(13)
	v_cvt_pk_bf16_f32 v74, v50, v51
	v_cvt_pk_bf16_f32 v75, v52, v53
	ds_write_b64 v249, v[74:75] offset:1152
	s_waitcnt vmcnt(12)
	v_cvt_pk_bf16_f32 v74, v54, v55
	v_cvt_pk_bf16_f32 v75, v56, v57
	ds_write_b64 v249, v[74:75] offset:1728
	s_waitcnt vmcnt(11)
	v_cvt_pk_bf16_f32 v74, v58, v59
	v_cvt_pk_bf16_f32 v75, v60, v61
	ds_write_b64 v249, v[74:75] offset:2304
	s_waitcnt vmcnt(10)
	v_cvt_pk_bf16_f32 v74, v62, v63
	v_cvt_pk_bf16_f32 v75, v64, v65
	ds_write_b64 v249, v[74:75] offset:2880
	s_waitcnt vmcnt(9)
	v_cvt_pk_bf16_f32 v74, v66, v67
	v_cvt_pk_bf16_f32 v75, v68, v69
	ds_write_b64 v249, v[74:75] offset:3456
	s_waitcnt vmcnt(8)
	v_cvt_pk_bf16_f32 v74, v70, v71
	v_cvt_pk_bf16_f32 v75, v72, v73
	ds_write_b64 v249, v[74:75] offset:4032
	s_waitcnt lgkmcnt(0)
	ds_read_b128 v[74:77], v250
	ds_read_b128 v[78:81], v250 offset:64
	s_waitcnt lgkmcnt(1)
	v_mfma_f32_16x16x32_bf16 v[74:77], v[74:77], v[2:5], 0
	ds_read_b128 v[82:85], v250 offset:2304
	s_waitcnt lgkmcnt(1)
	v_mfma_f32_16x16x32_bf16 v[74:77], v[78:81], v[6:9], v[74:77]
	ds_read_b128 v[78:81], v250 offset:2368
	s_waitcnt lgkmcnt(1)
	v_mfma_f32_16x16x32_bf16 v[82:85], v[82:85], v[2:5], 0
	s_waitcnt lgkmcnt(0)
	v_mfma_f32_16x16x32_bf16 v[78:81], v[78:81], v[6:9], v[82:85]
	s_nop 7
	v_cndmask_b32_e64 v233, v81, v77, s[2:3]
	v_cndmask_b32_e64 v232, v80, v76, s[2:3]
	v_cndmask_b32_e64 v235, v79, v75, s[2:3]
	v_cndmask_b32_e64 v234, v78, v74, s[2:3]
	s_waitcnt vmcnt(7)
	v_cvt_pk_bf16_f32 v74, v86, v87
	v_cvt_pk_bf16_f32 v75, v88, v89
	ds_write_b64 v249, v[74:75] offset:4608
	s_waitcnt vmcnt(6)
	v_cvt_pk_bf16_f32 v74, v90, v91
	v_cvt_pk_bf16_f32 v75, v92, v93
	ds_write_b64 v249, v[74:75] offset:5184
	s_waitcnt vmcnt(5)
	v_cvt_pk_bf16_f32 v74, v94, v95
	v_cvt_pk_bf16_f32 v75, v96, v97
	ds_write_b64 v249, v[74:75] offset:5760
	s_waitcnt vmcnt(4)
	v_cvt_pk_bf16_f32 v74, v98, v99
	v_cvt_pk_bf16_f32 v75, v100, v101
	ds_write_b64 v249, v[74:75] offset:6336
	s_waitcnt vmcnt(3)
	v_cvt_pk_bf16_f32 v74, v102, v103
	v_cvt_pk_bf16_f32 v75, v104, v105
	ds_write_b64 v249, v[74:75] offset:6912
	s_waitcnt vmcnt(2)
	v_cvt_pk_bf16_f32 v74, v106, v107
	v_cvt_pk_bf16_f32 v75, v108, v109
	ds_write_b64 v249, v[74:75] offset:7488
	s_waitcnt vmcnt(1)
	v_cvt_pk_bf16_f32 v74, v110, v111
	v_cvt_pk_bf16_f32 v75, v112, v113
	ds_write_b64 v249, v[74:75] offset:8064
	s_waitcnt vmcnt(0)
	v_cvt_pk_bf16_f32 v74, v114, v115
	v_cvt_pk_bf16_f32 v75, v116, v117
	ds_write_b64 v249, v[74:75] offset:8640
	s_waitcnt lgkmcnt(0)
	ds_read_b128 v[42:45], v250 offset:4608
	ds_read_b128 v[46:49], v250 offset:4672
	s_waitcnt lgkmcnt(1)
	v_mfma_f32_16x16x32_bf16 v[42:45], v[42:45], v[2:5], 0
	ds_read_b128 v[50:53], v250 offset:6912
	s_waitcnt lgkmcnt(1)
	v_mfma_f32_16x16x32_bf16 v[42:45], v[46:49], v[6:9], v[42:45]
	ds_read_b128 v[46:49], v250 offset:6976
	s_waitcnt lgkmcnt(1)
	v_mfma_f32_16x16x32_bf16 v[50:53], v[50:53], v[2:5], 0
	s_waitcnt lgkmcnt(0)
	v_mfma_f32_16x16x32_bf16 v[46:49], v[46:49], v[6:9], v[50:53]
	s_nop 7
	v_cndmask_b32_e64 v231, v49, v45, s[2:3]
	v_cndmask_b32_e64 v230, v48, v44, s[2:3]
	v_cndmask_b32_e64 v229, v47, v43, s[2:3]
	v_cndmask_b32_e64 v228, v46, v42, s[2:3]
	s_and_b32 s17, s6, 0xffff
	s_mov_b32 s18, s14
	s_mov_b32 s19, s15
	s_movk_i32 s6, 0x2000
	buffer_load_dwordx4 v[98:101], v248, s[16:19], 0 offen nt
	buffer_load_dwordx4 v[94:97], v248, s[16:19], s6 offen nt
	buffer_load_dwordx4 v[90:93], v248, s[16:19], s43 offen nt
	buffer_load_dwordx4 v[86:89], v248, s[16:19], s46 offen nt
	s_mov_b32 s6, 0xa000
	buffer_load_dwordx4 v[82:85], v248, s[16:19], s6 offen nt
	s_mov_b32 s6, 0xe000
	buffer_load_dwordx4 v[74:77], v248, s[16:19], s6 offen nt
	buffer_load_dwordx4 v[78:81], v248, s[16:19], s47 offen nt
	buffer_load_dwordx4 v[70:73], v248, s[16:19], s48 offen nt
	s_mov_b32 s6, 0x12000
	buffer_load_dwordx4 v[66:69], v248, s[16:19], s6 offen nt
	s_mov_b32 s6, 0x16000
	buffer_load_dwordx4 v[58:61], v248, s[16:19], s6 offen nt
	buffer_load_dwordx4 v[62:65], v248, s[16:19], s49 offen nt
	buffer_load_dwordx4 v[54:57], v248, s[16:19], s50 offen nt
	s_movk_i32 s6, 0x6000
	buffer_load_dwordx4 v[102:105], v248, s[16:19], s6 offen nt
	buffer_load_dwordx4 v[46:49], v248, s[16:19], s51 offen nt
	s_mov_b32 s6, 0x1a000
	buffer_load_dwordx4 v[50:53], v248, s[16:19], s6 offen nt
	s_mov_b32 s6, 0x1e000
	buffer_load_dwordx4 v[42:45], v248, s[16:19], s6 offen nt
	s_cmp_eq_u32 s39, s5
	s_mov_b64 s[6:7], -1
	s_cbranch_scc1 .LBB0_723
	v_pk_add_f32 v[124:125], v[144:145], v[204:205]
	v_pk_add_f32 v[122:123], v[142:143], v[206:207]
	v_pk_add_f32 v[120:121], v[144:145], v[208:209]
	v_pk_add_f32 v[118:119], v[142:143], v[210:211]
	v_pk_add_f32 v[116:117], v[144:145], v[212:213]
	v_pk_add_f32 v[114:115], v[142:143], v[214:215]
	v_pk_add_f32 v[112:113], v[144:145], v[216:217]
	v_pk_add_f32 v[110:111], v[142:143], v[218:219]
	v_pk_add_f32 v[108:109], v[144:145], v[220:221]
	v_pk_add_f32 v[106:107], v[142:143], v[222:223]
	v_pk_add_f32 v[128:129], v[144:145], v[224:225]
	v_pk_add_f32 v[126:127], v[142:143], v[226:227]
	v_pk_add_f32 v[132:133], v[144:145], v[232:233]
	v_pk_add_f32 v[130:131], v[142:143], v[234:235]
	v_pk_add_f32 v[136:137], v[144:145], v[230:231]
	v_pk_add_f32 v[134:135], v[142:143], v[228:229]
	s_mov_b64 s[6:7], 0
